# P2 general job queue: claim next job index during the current job (only while >768 jobs remain, to keep the tail balanced)
# baseline (speedup 1.0000x reference)
; __device__ __forceinline__ unsigned xcc_id() { return (unsigned)__builtin_amdgcn_s_getreg(20 | (3 << 11)) & 0xfu; }
; __device__ __forceinline__ unsigned cu_key() { return ((unsigned)__builtin_amdgcn_s_getreg(63492) >> 8) & 0xffu; }
; __global__ void __launch_bounds__(256, 2) fwd_megakernel(Params p) {
;     ...
;       int* cntG = (int*)(ws + OFF_CNT) + l + 2 * rep;
;       int* cntH = (int*)(ws + OFF_CNT) + 8 + l + 2 * rep;
;       int* claim = (int*)(ws + OFF_CLAIM) + (l + 2 * rep) * 2048;
;       const int nH = 256, nA = 1024, nAC = l == 0 ? 32 : 0, nHC = l == 0 ? 32 : 0, nP = l == 0 ? 528 : 512;
;       const int totalG = nA + nAC + nHC + nP;
;       int stage = 1;
;       if (tid == 0) {
;         unsigned key = xcc_id() * 256 + cu_key();
;         stage = (atomicAdd(&claim[key], 1) == 0) ? 0 : 1;
;       }
.LBB0_677:
	s_or_b64 exec, exec, s[0:1]
	s_mov_b32 s100, 0
	s_mov_b32 s2, s24
	s_mov_b32 s0, s24
	s_mov_b32 s1, s3
	v_writelane_b32 v239, s2, 63
	s_lshl_b64 s[0:1], s[0:1], 2
	s_nop 0
	v_writelane_b32 v238, s3, 0
	v_readlane_b32 s2, v237, 15
	s_add_u32 s6, s2, s0
	v_readlane_b32 s2, v237, 16
	s_addc_u32 s7, s2, s1
	v_readlane_b32 s2, v237, 17
	s_add_u32 s8, s2, s0
	v_readlane_b32 s0, v237, 18
	s_addc_u32 s9, s0, s1
	v_readlane_b32 s0, v237, 29
	v_readlane_b32 s1, v237, 30
	s_and_b64 s[0:1], s[0:1], exec
	s_cselect_b32 s80, 32, 0
	s_movk_i32 s0, 0x210
	s_cselect_b32 s0, s0, 0x200
	s_or_b32 s37, s80, 0x400
	s_add_i32 s1, s37, s80
	s_or_b32 s36, s1, s0
	s_branch .LBB0_679

; __global__ void __launch_bounds__(256, 2) fwd_megakernel(Params p) {
;     ...
;             } else if (stage == 1) {
;               int j = atomicAdd(cntG, 1);
;               if (j < totalG) { job = nH + j; break; }
;               stage = 2;
.LBB0_682:
	v_mov_b32_e32 v0, v152
	v_cmp_lt_i32_e32 vcc, 0, v0
	s_mov_b64 s[26:27], 0
	s_mov_b64 s[20:21], -1
	s_and_saveexec_b64 s[24:25], vcc
	s_xor_b64 s[24:25], exec, s[24:25]
	s_cbranch_execz .LBB0_688
	v_cmp_lt_i32_e32 vcc, 1, v0
	s_mov_b64 s[18:19], 0
	s_and_saveexec_b64 s[20:21], vcc
	s_xor_b64 s[20:21], exec, s[20:21]
	v_cmp_eq_u32_e32 vcc, 2, v0
	s_and_b64 s[26:27], vcc, exec
	s_or_saveexec_b64 s[20:21], s[20:21]
	s_mov_b64 s[28:29], -1
	s_mov_b64 s[22:23], -1
	s_xor_b64 exec, exec, s[20:21]
	s_cbranch_execz .LBB0_687
	s_cmp_lg_u32 s100, 0
	s_cbranch_scc1 .Lpop_pref
	v_mov_b64_e32 v[2:3], s[6:7]
	global_atomic_add v2, v[2:3], v198, off sc0
	s_branch .Lpop_join
.Lpop_pref:
	s_waitcnt vmcnt(0)
	v_mov_b32_e32 v2, v232
	s_mov_b32 s100, 0
.Lpop_join:
	s_xor_b64 s[22:23], exec, -1
	s_mov_b64 s[18:19], exec
	s_waitcnt vmcnt(0) lgkmcnt(0)
	v_cmp_gt_i32_e32 vcc, s36, v2
	s_nop 1
	s_add_i32 s101, s36, 0xfffffd00
	v_cmp_gt_i32_e64 s[28:29], s101, v2
	s_nop 1
	s_and_b64 s[28:29], s[28:29], exec
	s_cbranch_scc0 .Lpop_nopf
	v_mov_b64_e32 v[234:235], s[6:7]
	s_mov_b32 s100, 1
	global_atomic_add v232, v[234:235], v198, off sc0
.Lpop_nopf:
	s_orn2_b64 s[28:29], vcc, exec
